# grid barrier: releasing workgroup skips its own generation poll (on top of DMA-first K-loop, early inv, pipelined ret_scan)
# speedup vs baseline: 1.0005x; 1.0005x over previous
; __device__ __forceinline__ unsigned xb_ld(unsigned* p)              { return __hip_atomic_load(p, __ATOMIC_RELAXED, __HIP_MEMORY_SCOPE_AGENT); }
; __device__ __forceinline__ unsigned xb_add(unsigned* p, unsigned v) { return __hip_atomic_fetch_add(p, v, __ATOMIC_RELAXED, __HIP_MEMORY_SCOPE_AGENT); }
; #define XB_SPIN(cond, bar) do { unsigned _sp = 0; while (cond) { __builtin_amdgcn_s_sleep(1); \
;     if ((++_sp & 255u) == 0u) { if (xb_ld(&(bar)[XB_TMO])) break; if (_sp > XB_SPIN_CAP) { atomicAdd(&(bar)[XB_TMO], 1u); break; } } } } while (0)
; __device__ __forceinline__ void xcd_barrier(const XcdBarrier& b) {
;     ...
;         const unsigned old = xb_add(&bar[XB_XSUB(b.x)], 1u);
;         const unsigned gen = old / nloc;
;         if (old + 1u == (gen + 1u) * nloc) {
;             __builtin_amdgcn_fence(__ATOMIC_RELEASE, "agent");
;             asm volatile("s_waitcnt vmcnt(0)" ::: "memory");
;             const unsigned og = xb_add(&bar[XB_TOP], 1u);
;             const unsigned tg = og / nx;
;             if (og + 1u == (tg + 1u) * nx) {
; #pragma unroll
;                 for (unsigned j = 0; j < 16; ++j) (void)__hip_atomic_fetch_add(&bar[XB_XGEN(j)], 1u, __ATOMIC_RELAXED, __HIP_MEMORY_SCOPE_AGENT); }
;         }
;         XB_SPIN(xb_ld(&bar[XB_XGEN(b.x)]) == gen, bar);
.LBB0_1311:
	s_lshl_b32 s2, s5, 6
	s_add_i32 s76, s2, 0x500
	s_lshl_b64 s[0:1], s[76:77], 2
	s_add_u32 s0, s34, s0
	s_addc_u32 s1, s35, s1
	v_mov_b64_e32 v[4:5], s[0:1]
	v_mov_b32_e32 v7, 1
	flat_atomic_add v4, v[4:5], v7 sc0
	v_cvt_f32_u32_e32 v3, v2
	v_sub_u32_e32 v5, 0, v2
	v_rcp_iflag_f32_e32 v3, v3
	s_nop 0
	v_mul_f32_e32 v3, 0x4f7ffffe, v3
	v_cvt_u32_f32_e32 v3, v3
	v_mul_lo_u32 v5, v5, v3
	v_mul_hi_u32 v5, v3, v5
	v_add_u32_e32 v3, v3, v5
	s_waitcnt vmcnt(0) lgkmcnt(0)
	v_mul_hi_u32 v3, v4, v3
	v_mul_lo_u32 v5, v3, v2
	v_sub_u32_e32 v5, v4, v5
	v_cmp_ge_u32_e32 vcc, v5, v2
	v_add_u32_e32 v6, 1, v3
	s_nop 0
	v_cndmask_b32_e32 v3, v3, v6, vcc
	v_sub_u32_e32 v6, v5, v2
	v_cndmask_b32_e32 v5, v5, v6, vcc
	v_cmp_ge_u32_e32 vcc, v5, v2
	v_add_u32_e32 v5, 1, v3
	v_add_u32_e32 v6, 1, v4
	v_cndmask_b32_e32 v3, v3, v5, vcc
	v_mad_u64_u32 v[4:5], s[0:1], v2, v3, v[2:3]
	v_cmp_eq_u32_e32 vcc, v6, v4
	s_and_saveexec_b64 s[0:1], vcc
	s_cbranch_execz .LBB0_1314
	v_mov_b32_e32 v2, s34
	v_add_co_u32_e32 v4, vcc, 0x3000, v2
	v_mov_b32_e32 v2, s35
	buffer_wbl2 sc1
	s_waitcnt vmcnt(0)
	v_addc_co_u32_e32 v5, vcc, 0, v2, vcc
	flat_atomic_add v2, v[4:5], v7 offset:1024 sc0
	v_cvt_f32_u32_e32 v4, v0
	v_sub_u32_e32 v5, 0, v0
	v_rcp_iflag_f32_e32 v4, v4
	s_nop 0
	v_mul_f32_e32 v4, 0x4f7ffffe, v4
	v_cvt_u32_f32_e32 v4, v4
	v_mul_lo_u32 v5, v5, v4
	v_mul_hi_u32 v5, v4, v5
	v_add_u32_e32 v4, v4, v5
	s_waitcnt vmcnt(0) lgkmcnt(0)
	v_mul_hi_u32 v4, v2, v4
	v_mul_lo_u32 v5, v4, v0
	v_sub_u32_e32 v5, v2, v5
	v_cmp_ge_u32_e32 vcc, v5, v0
	v_add_u32_e32 v6, 1, v4
	v_add_u32_e32 v2, 1, v2
	v_cndmask_b32_e32 v4, v4, v6, vcc
	v_sub_u32_e32 v6, v5, v0
	v_cndmask_b32_e32 v5, v5, v6, vcc
	v_cmp_ge_u32_e32 vcc, v5, v0
	v_add_u32_e32 v5, 1, v4
	s_nop 0
	v_cndmask_b32_e32 v4, v4, v5, vcc
	v_mad_u64_u32 v[4:5], s[6:7], v0, v4, v[0:1]
	v_cmp_eq_u32_e32 vcc, v2, v4
	s_and_b64 exec, exec, vcc
	s_cbranch_execz .LBB0_1314
	v_mov_b32_e32 v0, s34
	v_add_co_u32_e32 v4, vcc, 0x2000, v0
	v_mov_b32_e32 v2, s35
	s_nop 0
	v_addc_co_u32_e32 v5, vcc, 0, v2, vcc
	flat_atomic_add v[4:5], v7 offset:1024
	flat_atomic_add v[4:5], v7 offset:1280
	flat_atomic_add v[4:5], v7 offset:1536
	flat_atomic_add v[4:5], v7 offset:1792
	flat_atomic_add v[4:5], v7 offset:2048
	flat_atomic_add v[4:5], v7 offset:2304
	flat_atomic_add v[4:5], v7 offset:2560
	flat_atomic_add v[4:5], v7 offset:2816
	flat_atomic_add v[4:5], v7 offset:3072
	flat_atomic_add v[4:5], v7 offset:3328
	flat_atomic_add v[4:5], v7 offset:3584
	flat_atomic_add v[4:5], v7 offset:3840
	v_add_co_u32_e32 v4, vcc, 0x3000, v0
	s_nop 1
	v_addc_co_u32_e32 v5, vcc, 0, v2, vcc
	flat_atomic_add v[4:5], v7
	flat_atomic_add v[4:5], v7 offset:256
	flat_atomic_add v[4:5], v7 offset:512
	flat_atomic_add v[4:5], v7 offset:768
	s_branch .LBB0_1325
